# lr_item all loads in flight; chunk-state U^T stored via wave-private LDS transpose (16B lanes, full lines)
# speedup vs baseline: 1.0188x; 1.0168x over previous
; __device__ __forceinline__ void lr_item(const Params& p, int l, int c, LAS unsigned char* lds) {
;     ...
;     const u16* xb = (const u16*)(ws + WS_XB) + (size_t)(c * 64) * 2048 + w * 256 + fq * 8;
;     const u16* wl = (const u16*)(ws + WS_WTIN) + ((size_t)l * NZROWS + 6144 + fr) * 2048 + w * 256 + fq * 8;
;     f32x4 acc[4];
; #pragma unroll
;     for (int mt = 0; mt < 4; ++mt) acc[mt] = (f32x4){0.f, 0.f, 0.f, 0.f};
; #pragma unroll
;     for (int kk = 0; kk < 8; ++kk) {
;         const bf16x8 bw = *(const bf16x8*)(wl + kk * 32);
; #pragma unroll
;         for (int mt = 0; mt < 4; ++mt) {
;             const bf16x8 a = *(const bf16x8*)(xb + (size_t)(mt * 16 + fr) * 2048 + kk * 32);
;             acc[mt] = __builtin_amdgcn_mfma_f32_16x16x32_bf16(a, bw, acc[mt], 0, 0, 0);
;         }
;     }
.LBB0_166:
	v_mov_b32_e32 v56, v200
	s_mov_b32 s6, s31
	s_ashr_i32 s13, s12, 31
	s_lshl_b64 s[10:11], s[12:13], 12
	s_mul_i32 s14, s6, 0x1900
	s_mul_hi_i32 s7, s6, 0x1900
	s_add_u32 s14, s14, 0x1800
	v_ashrrev_i32_e32 v57, 6, v56
	v_and_b32_e32 v58, 15, v56
	s_addc_u32 s7, s7, 0
	v_lshlrev_b32_e32 v2, 8, v57
	s_waitcnt vmcnt(0)
	v_or_b32_e32 v4, s14, v58
	v_mov_b32_e32 v5, s7
	v_ashrrev_i32_e32 v3, 31, v2
	v_lshlrev_b64 v[4:5], 12, v[4:5]
	s_add_u32 s10, s52, s10
	v_bfe_u32 v59, v56, 4, 2
	v_lshl_add_u64 v[4:5], s[58:59], 0, v[4:5]
	v_lshlrev_b64 v[2:3], 1, v[2:3]
	s_addc_u32 s11, s53, s11
	v_lshl_add_u64 v[4:5], v[4:5], 0, v[2:3]
	v_lshl_add_u64 v[2:3], s[10:11], 0, v[2:3]
	v_lshlrev_b32_e32 v0, 4, v59
	v_lshl_add_u64 v[2:3], v[2:3], 0, v[0:1]
	s_waitcnt vmcnt(5)
	v_lshl_add_u64 v[8:9], v[4:5], 0, v[0:1]
	v_lshlrev_b32_e32 v0, 12, v58
	v_or_b32_e32 v6, 0x10000, v0
	v_mov_b32_e32 v7, v1
	v_lshl_add_u64 v[4:5], v[2:3], 0, v[6:7]
	v_lshl_add_u64 v[244:245], v[2:3], 0, v[0:1]
	s_mov_b64 s[98:99], 0x10000
	v_lshl_add_u64 v[246:247], v[244:245], 0, s[98:99]
	v_lshl_add_u64 v[248:249], v[246:247], 0, s[98:99]
	v_lshl_add_u64 v[250:251], v[248:249], 0, s[98:99]
	global_load_dwordx4 v[60:63], v[8:9], off
	global_load_dwordx4 v[92:95], v[244:245], off
	global_load_dwordx4 v[96:99], v[246:247], off
	global_load_dwordx4 v[100:103], v[248:249], off
	global_load_dwordx4 v[104:107], v[250:251], off
	global_load_dwordx4 v[64:67], v[8:9], off offset:64
	global_load_dwordx4 v[108:111], v[244:245], off offset:64
	global_load_dwordx4 v[112:115], v[246:247], off offset:64
	global_load_dwordx4 v[116:119], v[248:249], off offset:64
	global_load_dwordx4 v[120:123], v[250:251], off offset:64
	global_load_dwordx4 v[68:71], v[8:9], off offset:128
	global_load_dwordx4 v[124:127], v[244:245], off offset:128
	global_load_dwordx4 v[128:131], v[246:247], off offset:128
	global_load_dwordx4 v[146:149], v[248:249], off offset:128
	global_load_dwordx4 v[150:153], v[250:251], off offset:128
	global_load_dwordx4 v[72:75], v[8:9], off offset:192
	global_load_dwordx4 v[154:157], v[244:245], off offset:192
	global_load_dwordx4 v[158:161], v[246:247], off offset:192
	global_load_dwordx4 v[162:165], v[248:249], off offset:192
	global_load_dwordx4 v[166:169], v[250:251], off offset:192
	global_load_dwordx4 v[76:79], v[8:9], off offset:256
	global_load_dwordx4 v[170:173], v[244:245], off offset:256
	global_load_dwordx4 v[174:177], v[246:247], off offset:256
	global_load_dwordx4 v[178:181], v[248:249], off offset:256
	global_load_dwordx4 v[184:187], v[250:251], off offset:256
	global_load_dwordx4 v[80:83], v[8:9], off offset:320
	global_load_dwordx4 v[188:191], v[244:245], off offset:320
	global_load_dwordx4 v[192:195], v[246:247], off offset:320
	global_load_dwordx4 v[196:199], v[248:249], off offset:320
	global_load_dwordx4 v[208:211], v[250:251], off offset:320
	global_load_dwordx4 v[84:87], v[8:9], off offset:384
	global_load_dwordx4 v[212:215], v[244:245], off offset:384
	global_load_dwordx4 v[216:219], v[246:247], off offset:384
	global_load_dwordx4 v[220:223], v[248:249], off offset:384
	global_load_dwordx4 v[224:227], v[250:251], off offset:384
	global_load_dwordx4 v[88:91], v[8:9], off offset:448
	global_load_dwordx4 v[228:231], v[244:245], off offset:448
	global_load_dwordx4 v[232:235], v[246:247], off offset:448
	global_load_dwordx4 v[236:239], v[248:249], off offset:448
	global_load_dwordx4 v[240:243], v[250:251], off offset:448
	s_mul_hi_i32 s7, s6, 0x21000
	s_mul_i32 s6, s6, 0x21000
	s_add_u32 s10, s80, s6
	s_addc_u32 s11, s81, s7
	s_lshl_b64 s[6:7], s[12:13], 3
	s_add_u32 s6, s10, s6
	s_addc_u32 s7, s11, s7
	s_waitcnt vmcnt(38)
	v_mfma_f32_16x16x32_bf16 v[6:9], v[92:95], v[60:63], 0
	s_waitcnt vmcnt(37)
	v_mfma_f32_16x16x32_bf16 v[16:19], v[96:99], v[60:63], 0
	s_waitcnt vmcnt(36)
	v_mfma_f32_16x16x32_bf16 v[2:5], v[100:103], v[60:63], 0
	s_waitcnt vmcnt(35)
	v_mfma_f32_16x16x32_bf16 v[10:13], v[104:107], v[60:63], 0
	s_waitcnt vmcnt(33)
	v_mfma_f32_16x16x32_bf16 v[6:9], v[108:111], v[64:67], v[6:9]
	s_waitcnt vmcnt(32)
	v_mfma_f32_16x16x32_bf16 v[16:19], v[112:115], v[64:67], v[16:19]
	s_waitcnt vmcnt(31)
	v_mfma_f32_16x16x32_bf16 v[2:5], v[116:119], v[64:67], v[2:5]
	s_waitcnt vmcnt(30)
	v_mfma_f32_16x16x32_bf16 v[10:13], v[120:123], v[64:67], v[10:13]
	s_waitcnt vmcnt(28)
; #define LAS __attribute__((address_space(3)))
; __device__ __forceinline__ float rstd_of(u64 s) { return rsqrtf((float)s * SS_INV + EPS); }
; __device__ __forceinline__ void lr_item(const Params& p, int l, int c, LAS unsigned char* lds) {
;     ...
;     for (int kk = 0; kk < 8; ++kk) {
;         const bf16x8 bw = *(const bf16x8*)(wl + kk * 32);
; #pragma unroll
;         for (int mt = 0; mt < 4; ++mt) {
;             const bf16x8 a = *(const bf16x8*)(xb + (size_t)(mt * 16 + fr) * 2048 + kk * 32);
;             acc[mt] = __builtin_amdgcn_mfma_f32_16x16x32_bf16(a, bw, acc[mt], 0, 0, 0);
;         }
;     }
;     LAS float* red = (LAS float*)lds;
; #pragma unroll
;     for (int mt = 0; mt < 4; ++mt)
; #pragma unroll
;         for (int e = 0; e < 4; ++e) red[w * 1024 + (mt * 16 + fq * 4 + e) * 16 + fr] = acc[mt][e];
;     __syncthreads();
;     {
;         const int o = tid * 2, t = o >> 4;
;         float s0 = 0.f, s1 = 0.f;
; #pragma unroll
;         for (int ww = 0; ww < 8; ++ww) { s0 += red[ww * 1024 + o]; s1 += red[ww * 1024 + o + 1]; }
;         const float rs = rstd_of(((const u64*)(ws + WS_SUMSQ))[(size_t)l * T + c * 64 + t]);
;         float* zl = (float*)(ws + WS_ZLR) + (size_t)(c * 64) * 16 + o;
;         zl[0] = s0 * rs; zl[1] = s1 * rs;
	v_mfma_f32_16x16x32_bf16 v[6:9], v[124:127], v[68:71], v[6:9]
	s_waitcnt vmcnt(27)
	v_mfma_f32_16x16x32_bf16 v[16:19], v[128:131], v[68:71], v[16:19]
	s_waitcnt vmcnt(26)
	v_mfma_f32_16x16x32_bf16 v[2:5], v[146:149], v[68:71], v[2:5]
	s_waitcnt vmcnt(25)
	v_mfma_f32_16x16x32_bf16 v[10:13], v[150:153], v[68:71], v[10:13]
	s_waitcnt vmcnt(23)
	v_mfma_f32_16x16x32_bf16 v[6:9], v[154:157], v[72:75], v[6:9]
	s_waitcnt vmcnt(22)
	v_mfma_f32_16x16x32_bf16 v[16:19], v[158:161], v[72:75], v[16:19]
	s_waitcnt vmcnt(21)
	v_mfma_f32_16x16x32_bf16 v[2:5], v[162:165], v[72:75], v[2:5]
	s_waitcnt vmcnt(20)
	v_mfma_f32_16x16x32_bf16 v[10:13], v[166:169], v[72:75], v[10:13]
	s_waitcnt vmcnt(18)
	v_mfma_f32_16x16x32_bf16 v[6:9], v[170:173], v[76:79], v[6:9]
	s_waitcnt vmcnt(17)
	v_mfma_f32_16x16x32_bf16 v[16:19], v[174:177], v[76:79], v[16:19]
	s_waitcnt vmcnt(16)
	v_mfma_f32_16x16x32_bf16 v[2:5], v[178:181], v[76:79], v[2:5]
	s_waitcnt vmcnt(15)
	v_mfma_f32_16x16x32_bf16 v[10:13], v[184:187], v[76:79], v[10:13]
	s_waitcnt vmcnt(13)
	v_mfma_f32_16x16x32_bf16 v[6:9], v[188:191], v[80:83], v[6:9]
	s_waitcnt vmcnt(12)
	v_mfma_f32_16x16x32_bf16 v[16:19], v[192:195], v[80:83], v[16:19]
	s_waitcnt vmcnt(11)
	v_mfma_f32_16x16x32_bf16 v[2:5], v[196:199], v[80:83], v[2:5]
	s_waitcnt vmcnt(10)
	v_mfma_f32_16x16x32_bf16 v[10:13], v[208:211], v[80:83], v[10:13]
	s_waitcnt vmcnt(8)
	v_mfma_f32_16x16x32_bf16 v[6:9], v[212:215], v[84:87], v[6:9]
	s_waitcnt vmcnt(7)
	v_mfma_f32_16x16x32_bf16 v[16:19], v[216:219], v[84:87], v[16:19]
	s_waitcnt vmcnt(6)
	v_mfma_f32_16x16x32_bf16 v[2:5], v[220:223], v[84:87], v[2:5]
	s_waitcnt vmcnt(5)
	v_mfma_f32_16x16x32_bf16 v[10:13], v[224:227], v[84:87], v[10:13]
	s_waitcnt vmcnt(3)
	v_mfma_f32_16x16x32_bf16 v[6:9], v[228:231], v[88:91], v[6:9]
	s_waitcnt vmcnt(2)
	v_mfma_f32_16x16x32_bf16 v[16:19], v[232:235], v[88:91], v[16:19]
	s_waitcnt vmcnt(1)
	v_mfma_f32_16x16x32_bf16 v[2:5], v[236:239], v[88:91], v[2:5]
	s_waitcnt vmcnt(0)
	v_mfma_f32_16x16x32_bf16 v[10:13], v[240:243], v[88:91], v[10:13]
	v_lshlrev_b32_e32 v0, 8, v59
	s_nop 7
	s_nop 2
	v_lshl_add_u32 v14, v57, 12, 0
	v_lshlrev_b32_e32 v15, 2, v58
	v_add3_u32 v0, v14, v15, v0
	ds_write2_b32 v0, v6, v7 offset1:16
	ds_write2_b32 v0, v8, v9 offset0:32 offset1:48
	v_add_u32_e32 v6, 0x400, v0
	ds_write2_b32 v6, v16, v17 offset1:16
	ds_write2_b32 v6, v18, v19 offset0:32 offset1:48
	v_add_u32_e32 v6, 0x800, v0
	ds_write2_b32 v6, v2, v3 offset1:16
	ds_write2_b32 v6, v4, v5 offset0:32 offset1:48
	v_ashrrev_i32_e32 v2, 3, v56
	v_ashrrev_i32_e32 v3, 31, v2
	v_add_u32_e32 v0, 0xc00, v0
	v_lshl_add_u64 v[2:3], v[2:3], 3, s[6:7]
	ds_write2_b32 v0, v10, v11 offset1:16
	ds_write2_b32 v0, v12, v13 offset0:32 offset1:48
	s_waitcnt lgkmcnt(0)
	s_barrier
	global_load_dwordx2 v[18:19], v[2:3], off
	s_lshl_b64 s[6:7], s[12:13], 6
	v_lshlrev_b32_e32 v2, 1, v56
	s_add_u32 s6, s72, s6
	v_lshl_add_u32 v0, v56, 3, 0
	v_ashrrev_i32_e32 v3, 31, v2
	s_addc_u32 s7, s73, s7
	v_lshl_add_u64 v[20:21], v[2:3], 2, s[6:7]
	ds_read2st64_b64 v[2:5], v0 offset1:8
	ds_read2st64_b64 v[6:9], v0 offset0:16 offset1:24
	ds_read2st64_b64 v[10:13], v0 offset0:32 offset1:40
	ds_read2st64_b64 v[14:17], v0 offset0:48 offset1:56
	s_add_i32 s2, s2, s3
	s_add_i32 s12, s12, s91
	s_cmpk_lt_i32 s2, 0x100
	s_waitcnt lgkmcnt(3)
	v_pk_add_f32 v[2:3], v[2:3], 0 op_sel_hi:[1,0]
	s_waitcnt vmcnt(0)
	v_ffbh_u32_e32 v0, v19
	v_min_u32_e32 v0, 32, v0
	v_pk_add_f32 v[2:3], v[2:3], v[4:5]
	v_lshlrev_b64 v[4:5], v0, v[18:19]
	v_min_u32_e32 v4, 1, v4
	v_or_b32_e32 v4, v5, v4
	v_cvt_f32_u32_e32 v4, v4
	v_sub_u32_e32 v0, 32, v0
	s_waitcnt lgkmcnt(2)
	v_pk_add_f32 v[2:3], v[2:3], v[6:7]
	v_ldexp_f32 v0, v4, v0
	v_fmamk_f32 v0, v0, 0x30000000, v203
	v_mul_f32_e32 v4, 0x4b800000, v0
	v_cmp_gt_f32_e32 vcc, s89, v0
	v_pk_add_f32 v[2:3], v[2:3], v[8:9]
	s_nop 0
	v_cndmask_b32_e32 v0, v0, v4, vcc
	v_rsq_f32_e32 v0, v0
	s_waitcnt lgkmcnt(1)
	v_pk_add_f32 v[2:3], v[2:3], v[10:11]
	v_mul_f32_e32 v4, 0x45800000, v0
	v_pk_add_f32 v[2:3], v[2:3], v[12:13]
	v_cndmask_b32_e32 v0, v0, v4, vcc
	s_waitcnt lgkmcnt(0)
	v_pk_add_f32 v[2:3], v[2:3], v[14:15]
	s_nop 0
	v_pk_add_f32 v[2:3], v[2:3], v[16:17]
	s_nop 0
	v_pk_mul_f32 v[2:3], v[2:3], v[0:1] op_sel_hi:[1,0]
	global_store_dwordx2 v[20:21], v[2:3], off
	s_barrier
	s_cbranch_scc1 .LBB0_166

; #define LAS __attribute__((address_space(3)))
; __device__ __forceinline__ unsigned cvt_pk_bf16(float lo, float hi) { unsigned r; asm("v_cvt_pk_bf16_f32 %0, %1, %2" : "=v"(r) : "v"(lo), "v"(hi)); return r; }
; __device__ __forceinline__ void gla_local_item(const Params& p, int l, int c, int h, LAS unsigned char* lds) {
;     ...
;     for (int kk = 0; kk < 2; ++kk) {
; #pragma unroll
;         for (int mt = 0; mt < 8; ++mt) {
;             const bf16x8 a = *(const LAS bf16x8*)(kT + (mt * 16 + fr) * 144 + (kk * 32 + fq * 8) * 2);
; #pragma unroll
;             for (int n = 0; n < 2; ++n) acc[mt][n] = __builtin_amdgcn_mfma_f32_16x16x32_bf16(a, bv[kk][n], acc[mt][n], 0, 0, 0);
;         }
;     }
;     if (c < 256) {
;         u16* ut = (u16*)(ws + WS_UT) + (size_t)(c * 4 + h) * 32768;
; #pragma unroll
;         for (int mt = 0; mt < 8; ++mt)
; #pragma unroll
;             for (int n = 0; n < 2; ++n) {
;                 u32x2 wv; wv.x = cvt_pk_bf16(acc[mt][n][0], acc[mt][n][1]); wv.y = cvt_pk_bf16(acc[mt][n][2], acc[mt][n][3]);
;                 *(u32x2*)(ut + (w * 32 + n * 16 + fr) * 128 + mt * 16 + fq * 4) = wv;
;             }
.LBB0_502:
	s_or_b64 exec, exec, s[0:1]
	v_mul_u32_u24_e32 v18, 0x90, v26
	v_add3_u32 v0, 0, v0, v18
	s_waitcnt lgkmcnt(0)
	s_barrier
	ds_read_b128 v[22:25], v0 offset:4096
	ds_read_b128 v[34:37], v0 offset:6400
	ds_read_b128 v[42:45], v0 offset:8704
	ds_read_b128 v[50:53], v0 offset:11008
	ds_read_b128 v[58:61], v0 offset:13312
	ds_read_b128 v[66:69], v0 offset:15616
	ds_read_b128 v[74:77], v0 offset:17920
	ds_read_b128 v[82:85], v0 offset:20224
	s_waitcnt lgkmcnt(7)
	v_mfma_f32_16x16x32_bf16 v[30:33], v[22:25], v[10:13], 0
	s_add_u32 s14, s14, s22
	s_addc_u32 s15, s15, 0
	s_add_i32 s6, s6, s7
	v_mfma_f32_16x16x32_bf16 v[22:25], v[22:25], v[14:17], 0
	s_add_u32 s16, s16, s90
	s_addc_u32 s17, s17, 0
	s_cmp_ge_i32 s14, s23
	s_waitcnt lgkmcnt(6)
	v_mfma_f32_16x16x32_bf16 v[38:41], v[34:37], v[10:13], 0
	v_mfma_f32_16x16x32_bf16 v[34:37], v[34:37], v[14:17], 0
	s_waitcnt lgkmcnt(5)
	v_mfma_f32_16x16x32_bf16 v[46:49], v[42:45], v[10:13], 0
	v_mfma_f32_16x16x32_bf16 v[42:45], v[42:45], v[14:17], 0
	s_waitcnt lgkmcnt(4)
	v_mfma_f32_16x16x32_bf16 v[54:57], v[50:53], v[10:13], 0
	v_mfma_f32_16x16x32_bf16 v[50:53], v[50:53], v[14:17], 0
	s_waitcnt lgkmcnt(3)
	v_mfma_f32_16x16x32_bf16 v[62:65], v[58:61], v[10:13], 0
	v_mfma_f32_16x16x32_bf16 v[58:61], v[58:61], v[14:17], 0
	s_waitcnt lgkmcnt(2)
	v_mfma_f32_16x16x32_bf16 v[70:73], v[66:69], v[10:13], 0
	v_mfma_f32_16x16x32_bf16 v[66:69], v[66:69], v[14:17], 0
	s_waitcnt lgkmcnt(1)
	v_mfma_f32_16x16x32_bf16 v[78:81], v[74:77], v[10:13], 0
	v_mfma_f32_16x16x32_bf16 v[74:77], v[74:77], v[14:17], 0
	s_waitcnt lgkmcnt(0)
	v_mfma_f32_16x16x32_bf16 v[10:13], v[82:85], v[10:13], 0
	v_mfma_f32_16x16x32_bf16 v[14:17], v[82:85], v[14:17], 0
	ds_read_b128 v[82:85], v0 offset:4160
	s_waitcnt lgkmcnt(0)
	v_mfma_f32_16x16x32_bf16 v[30:33], v[82:85], v[2:5], v[30:33]
	v_mfma_f32_16x16x32_bf16 v[22:25], v[82:85], v[6:9], v[22:25]
	ds_read_b128 v[82:85], v0 offset:6464
	s_waitcnt lgkmcnt(0)
	v_mfma_f32_16x16x32_bf16 v[38:41], v[82:85], v[2:5], v[38:41]
	v_mfma_f32_16x16x32_bf16 v[34:37], v[82:85], v[6:9], v[34:37]
	ds_read_b128 v[82:85], v0 offset:8768
	s_waitcnt lgkmcnt(0)
	v_mfma_f32_16x16x32_bf16 v[46:49], v[82:85], v[2:5], v[46:49]
	v_mfma_f32_16x16x32_bf16 v[42:45], v[82:85], v[6:9], v[42:45]
	ds_read_b128 v[82:85], v0 offset:11072
	s_waitcnt lgkmcnt(0)
	v_mfma_f32_16x16x32_bf16 v[54:57], v[82:85], v[2:5], v[54:57]
	v_mfma_f32_16x16x32_bf16 v[50:53], v[82:85], v[6:9], v[50:53]
	ds_read_b128 v[82:85], v0 offset:13376
	s_waitcnt lgkmcnt(0)
	v_mfma_f32_16x16x32_bf16 v[62:65], v[82:85], v[2:5], v[62:65]
	v_mfma_f32_16x16x32_bf16 v[58:61], v[82:85], v[6:9], v[58:61]
	ds_read_b128 v[82:85], v0 offset:15680
	s_waitcnt lgkmcnt(0)
	v_mfma_f32_16x16x32_bf16 v[70:73], v[82:85], v[2:5], v[70:73]
	v_mfma_f32_16x16x32_bf16 v[66:69], v[82:85], v[6:9], v[66:69]
	ds_read_b128 v[82:85], v0 offset:17984
	s_waitcnt lgkmcnt(0)
	v_mfma_f32_16x16x32_bf16 v[78:81], v[82:85], v[2:5], v[78:81]
	v_mfma_f32_16x16x32_bf16 v[74:77], v[82:85], v[6:9], v[74:77]
	ds_read_b128 v[82:85], v0 offset:20288
	v_lshlrev_b32_e32 v0, 3, v27
	s_waitcnt lgkmcnt(0)
	v_mfma_f32_16x16x32_bf16 v[2:5], v[82:85], v[2:5], v[10:13]
	s_nop 2
	v_lshlrev_b64 v[10:11], 16, v[20:21]
	v_lshl_add_u64 v[10:11], s[66:67], 0, v[10:11]
	v_lshl_add_u64 v[10:11], v[10:11], 0, v[0:1]
	v_mfma_f32_16x16x32_bf16 v[6:9], v[82:85], v[6:9], v[14:17]
	s_nop 3
	v_lshrrev_b32_e32 v12, 6, v200
	v_mul_u32_u24_e32 v12, 0x2200, v12
	v_add_u32_e32 v12, 0x6000, v12
	v_mov_b32_e32 v13, 0x110
	v_mad_u32_u24 v10, v26, v13, v12
	v_lshl_add_u32 v10, v27, 3, v10
	v_and_b32_e32 v14, 63, v200
	v_lshrrev_b32_e32 v15, 4, v14
	v_and_b32_e32 v14, 15, v14
	v_mad_u32_u24 v11, v15, v13, v12
	v_lshl_add_u32 v11, v14, 4, v11
	v_lshlrev_b64 v[16:17], 16, v[20:21]
	v_lshl_add_u64 v[16:17], s[66:67], 0, v[16:17]
	v_lshrrev_b32_e32 v12, 6, v200
	v_lshlrev_b32_e32 v12, 13, v12
	v_lshl_add_u32 v12, v15, 8, v12
	v_lshl_add_u32 v12, v14, 4, v12
	v_mov_b32_e32 v13, 0
	v_lshl_add_u64 v[16:17], v[16:17], 0, v[12:13]
	s_mov_b64 s[98:99], 0x1000
	v_lshl_add_u64 v[18:19], v[16:17], 0, s[98:99]
	v_cvt_pk_bf16_f32 v30, v30, v31
	v_cvt_pk_bf16_f32 v31, v32, v33
	v_cvt_pk_bf16_f32 v22, v22, v23
	v_cvt_pk_bf16_f32 v23, v24, v25
	v_cvt_pk_bf16_f32 v38, v38, v39
	v_cvt_pk_bf16_f32 v39, v40, v41
	v_cvt_pk_bf16_f32 v34, v34, v35
	v_cvt_pk_bf16_f32 v35, v36, v37
	v_cvt_pk_bf16_f32 v46, v46, v47
	v_cvt_pk_bf16_f32 v47, v48, v49
	v_cvt_pk_bf16_f32 v42, v42, v43
	v_cvt_pk_bf16_f32 v43, v44, v45
	v_cvt_pk_bf16_f32 v54, v54, v55
	v_cvt_pk_bf16_f32 v55, v56, v57
	v_cvt_pk_bf16_f32 v50, v50, v51
	v_cvt_pk_bf16_f32 v51, v52, v53
	v_cvt_pk_bf16_f32 v62, v62, v63
	v_cvt_pk_bf16_f32 v63, v64, v65
	v_cvt_pk_bf16_f32 v58, v58, v59
	v_cvt_pk_bf16_f32 v59, v60, v61
	v_cvt_pk_bf16_f32 v70, v70, v71
	v_cvt_pk_bf16_f32 v71, v72, v73
	v_cvt_pk_bf16_f32 v66, v66, v67
	v_cvt_pk_bf16_f32 v67, v68, v69
	v_cvt_pk_bf16_f32 v78, v78, v79
	v_cvt_pk_bf16_f32 v79, v80, v81
	v_cvt_pk_bf16_f32 v74, v74, v75
	v_cvt_pk_bf16_f32 v75, v76, v77
	v_cvt_pk_bf16_f32 v2, v2, v3
	v_cvt_pk_bf16_f32 v3, v4, v5
	v_cvt_pk_bf16_f32 v6, v6, v7
	v_cvt_pk_bf16_f32 v7, v8, v9
	ds_write_b64 v10, v[30:31]
	ds_write_b64 v10, v[22:23] offset:4352
	ds_write_b64 v10, v[38:39] offset:32
	ds_write_b64 v10, v[34:35] offset:4384
	ds_write_b64 v10, v[46:47] offset:64
	ds_write_b64 v10, v[42:43] offset:4416
	ds_write_b64 v10, v[54:55] offset:96
	ds_write_b64 v10, v[50:51] offset:4448
	ds_write_b64 v10, v[62:63] offset:128
	ds_write_b64 v10, v[58:59] offset:4480
	ds_write_b64 v10, v[70:71] offset:160
	ds_write_b64 v10, v[66:67] offset:4512
	ds_write_b64 v10, v[78:79] offset:192
	ds_write_b64 v10, v[74:75] offset:4544
	ds_write_b64 v10, v[2:3] offset:224
	ds_write_b64 v10, v[6:7] offset:4576
	s_waitcnt lgkmcnt(0)
	ds_read_b128 v[30:33], v11
	ds_read_b128 v[34:37], v11 offset:1088
	ds_read_b128 v[38:41], v11 offset:2176
	ds_read_b128 v[42:45], v11 offset:3264
	ds_read_b128 v[46:49], v11 offset:4352
	ds_read_b128 v[50:53], v11 offset:5440
	ds_read_b128 v[54:57], v11 offset:6528
	ds_read_b128 v[58:61], v11 offset:7616
	s_waitcnt lgkmcnt(7)
	global_store_dwordx4 v[16:17], v[30:33], off
	s_waitcnt lgkmcnt(6)
	global_store_dwordx4 v[16:17], v[34:37], off offset:1024
	s_waitcnt lgkmcnt(5)
	global_store_dwordx4 v[16:17], v[38:41], off offset:2048
	s_waitcnt lgkmcnt(4)
	global_store_dwordx4 v[16:17], v[42:45], off offset:3072
	s_waitcnt lgkmcnt(3)
	global_store_dwordx4 v[18:19], v[46:49], off
	s_waitcnt lgkmcnt(2)
	global_store_dwordx4 v[18:19], v[50:53], off offset:1024
	s_waitcnt lgkmcnt(1)
	global_store_dwordx4 v[18:19], v[54:57], off offset:2048
	s_waitcnt lgkmcnt(0)
	global_store_dwordx4 v[18:19], v[58:61], off offset:3072
	s_barrier
	s_cbranch_scc1 .LBB0_352
